# v68 + barrier 1: XSUB arrival atomic issued before the XCC census loads (census overlaps the arrival round trip)
# baseline (speedup 1.0000x reference)
.LBB0_225:
	s_or_b64 exec, exec, s[36:37]
	v_mbcnt_lo_u32_b32 v0, -1, 0
	v_mbcnt_hi_u32_b32 v0, -1, v0
	s_waitcnt vmcnt(0)
	v_readlane_b32 s0, v254, 3
	s_sub_i32 s0, 0, s0
	s_nop 0
	v_writelane_b32 v254, s0, 13
	v_cmp_eq_u32_e32 vcc, s0, v0
	s_barrier
	s_and_saveexec_b64 s[0:1], vcc
	s_cbranch_execz .LBB0_277
	s_add_i32 s2, 0, 0x27f20
	v_mov_b32_e32 v0, s2
	s_waitcnt vmcnt(0) expcnt(0) lgkmcnt(0)
	v_readlane_b32 s18, v254, 8
	v_readlane_b32 s6, v254, 6
	v_readlane_b32 s7, v254, 7
	v_mov_b32_e32 v18, 1
	v_mov_b32_e32 v19, 0
	s_lshl_b32 s18, s18, 8
	s_add_u32 s18, s6, s18
	s_addc_u32 s19, s7, 0
	s_add_u32 s18, s18, 0x1400
	s_addc_u32 s19, s19, 0
	global_atomic_add v20, v19, v18, s[18:19] sc0
	ds_read_b32 v2, v0
	s_add_i32 s2, 0, 0x27f24
	v_mov_b32_e32 v0, s2
	ds_read_b32 v0, v0
	s_waitcnt lgkmcnt(1)
	v_cmp_ne_u32_e32 vcc, 0, v2
	s_cbranch_vccnz .LBB0_241
	v_readlane_b32 s2, v254, 9
	v_readlane_b32 s3, v254, 10
	s_load_dwordx2 s[6:7], s[2:3], 0x4
	v_readlane_b32 s36, v254, 4
	v_readlane_b32 s37, v254, 5
	s_add_u32 s2, s36, 0x4200
	s_addc_u32 s3, s37, 0
	s_add_u32 s4, s36, 0x4400
	s_addc_u32 s5, s37, 0
	s_waitcnt lgkmcnt(0)
	s_mul_i32 s33, s6, s56
	s_add_u32 s6, s36, 0x4500
	s_mul_i32 s33, s33, s7
	s_addc_u32 s7, s37, 0
	s_add_u32 s8, s36, 0x4600
	s_addc_u32 s9, s37, 0
	s_add_u32 s10, s36, 0x4700
	s_addc_u32 s11, s37, 0
	s_add_u32 s12, s36, 0x4800
	s_addc_u32 s13, s37, 0
	s_add_u32 s14, s36, 0x4900
	s_addc_u32 s15, s37, 0
	s_add_u32 s16, s36, 0x4a00
	s_addc_u32 s17, s37, 0
	s_add_u32 s18, s36, 0x4b00
	s_addc_u32 s19, s37, 0
	s_add_u32 s20, s36, 0x4c00
	s_addc_u32 s21, s37, 0
	s_add_u32 s22, s36, 0x4d00
	s_addc_u32 s23, s37, 0
	s_add_u32 s24, s36, 0x4e00
	s_addc_u32 s25, s37, 0
	s_add_u32 s26, s36, 0x4f00
	s_addc_u32 s27, s37, 0
	s_add_u32 s28, s36, 0x5000
	s_addc_u32 s29, s37, 0
	s_add_u32 s30, s36, 0x5100
	s_addc_u32 s31, s37, 0
	s_add_u32 s34, s36, 0x5200
	s_addc_u32 s35, s37, 0
	s_add_u32 s36, s36, 0x5300
	s_addc_u32 s37, s37, 0
	s_mov_b32 s44, 1
	v_mov_b32_e32 v16, 0
	s_branch .LBB0_229

.LBB0_241:
	v_readlane_b32 s2, v254, 8
	v_readlane_b32 s6, v254, 6
	v_readlane_b32 s7, v254, 7
	v_readlane_b32 s4, v254, 4
	v_readlane_b32 s5, v254, 5
	s_lshl_b32 s2, s2, 8
	s_add_u32 s2, s6, s2
	s_addc_u32 s3, s7, 0
	s_add_u32 s8, s2, 0x2400
	s_addc_u32 s9, s3, 0
	s_add_u32 s2, s2, 0x1400
	s_addc_u32 s3, s3, 0
	s_add_u32 s14, s4, 0x4200
	s_addc_u32 s15, s5, 0
	s_add_u32 s16, s4, 0x7400
	s_addc_u32 s17, s5, 0
	s_add_u32 s18, s6, 0x2400
	s_addc_u32 s19, s7, 0
	v_mov_b32_e32 v4, 1
	v_mov_b32_e32 v5, 0
	s_waitcnt vmcnt(0) lgkmcnt(0)
	v_readfirstlane_b32 s10, v2
	v_readfirstlane_b32 s11, v0
	v_readfirstlane_b32 s12, v20
	s_add_i32 s12, s12, 1
	s_cmp_lg_u32 s12, s10
	s_cbranch_scc1 .Lxb1_poll
	buffer_wbl2 sc1
	s_waitcnt vmcnt(0)
	global_atomic_add v3, v5, v4, s[16:17] sc0
	s_waitcnt vmcnt(0)
	v_readfirstlane_b32 s12, v3
	s_add_i32 s12, s12, 1
	s_cmp_lg_u32 s12, s11
	s_cbranch_scc1 .Lxb1_poll
	global_atomic_add v5, v4, s[18:19]
	global_atomic_add v5, v4, s[18:19] offset:256
	global_atomic_add v5, v4, s[18:19] offset:512
	global_atomic_add v5, v4, s[18:19] offset:768
	global_atomic_add v5, v4, s[18:19] offset:1024
	global_atomic_add v5, v4, s[18:19] offset:1280
	global_atomic_add v5, v4, s[18:19] offset:1536
	global_atomic_add v5, v4, s[18:19] offset:1792
	global_atomic_add v5, v4, s[18:19] offset:2048
	global_atomic_add v5, v4, s[18:19] offset:2304
	global_atomic_add v5, v4, s[18:19] offset:2560
	global_atomic_add v5, v4, s[18:19] offset:2816
	global_atomic_add v5, v4, s[18:19] offset:3072
	global_atomic_add v5, v4, s[18:19] offset:3328
	global_atomic_add v5, v4, s[18:19] offset:3584
	global_atomic_add v5, v4, s[18:19] offset:3840
	buffer_inv sc1
	s_waitcnt vmcnt(0)
	s_branch .Lxb1_out
